# P9 SwiGLU epilogue: in-place f32 g*sigmoid(g)*u with v_exp+v_rcp instead of IEEE div sequence
# baseline (speedup 1.0000x reference)
; DI unsigned pk_bf16(float lo, float hi) { f32x2v v = {lo, hi}; bf16x2v b = __builtin_convertvector(v, bf16x2v); return __builtin_bit_cast(unsigned, b); }
; DI float sigmoidf_(float x) { return 1.f / (1.f + __expf(-x)); }
; DI void phase9_10(const Params& p, char* smem) {
;     ...
;         for (int pr = 0; pr < 2; ++pr) {
;           char* d = tile + (wn * 64 + tn * 32 + r) * 272 + (wm * 64 + pr * 32 + 4 * hh) * 2;
; #pragma unroll
;           for (int q = 0; q < 4; ++q) {
;             float v[4];
; #pragma unroll
;             for (int j = 0; j < 4; ++j) { const float g = acc[2 * pr][tn][4 * q + j], uu = acc[2 * pr + 1][tn][4 * q + j]; v[j] = g * sigmoidf_(g) * uu; }
;             uint2 ou; ou.x = pk_bf16(v[0], v[1]); ou.y = pk_bf16(v[2], v[3]);
;             *(uint2*)(d + 16 * q) = ou;
;           }
.Lp9_nonext:
	s_setprio 0
	s_nop 7
	s_nop 3
	v_mul_f32_e32 v128, 0xbfb8aa3b, v112
	v_mul_f32_e32 v129, 0xbfb8aa3b, v113
	v_mul_f32_e32 v130, 0xbfb8aa3b, v114
	v_mul_f32_e32 v131, 0xbfb8aa3b, v115
	v_mul_f32_e32 v132, 0xbfb8aa3b, v116
	v_mul_f32_e32 v133, 0xbfb8aa3b, v117
	v_mul_f32_e32 v134, 0xbfb8aa3b, v118
	v_mul_f32_e32 v135, 0xbfb8aa3b, v119
	v_mul_f32_e32 v136, 0xbfb8aa3b, v120
	v_mul_f32_e32 v137, 0xbfb8aa3b, v121
	v_mul_f32_e32 v138, 0xbfb8aa3b, v122
	v_mul_f32_e32 v139, 0xbfb8aa3b, v123
	v_mul_f32_e32 v140, 0xbfb8aa3b, v124
	v_mul_f32_e32 v141, 0xbfb8aa3b, v125
	v_mul_f32_e32 v142, 0xbfb8aa3b, v126
	v_mul_f32_e32 v143, 0xbfb8aa3b, v127
	v_exp_f32_e32 v128, v128
	v_exp_f32_e32 v129, v129
	v_exp_f32_e32 v130, v130
	v_exp_f32_e32 v131, v131
	v_exp_f32_e32 v132, v132
	v_exp_f32_e32 v133, v133
	v_exp_f32_e32 v134, v134
	v_exp_f32_e32 v135, v135
	v_exp_f32_e32 v136, v136
	v_exp_f32_e32 v137, v137
	v_exp_f32_e32 v138, v138
	v_exp_f32_e32 v139, v139
	v_exp_f32_e32 v140, v140
	v_exp_f32_e32 v141, v141
	v_exp_f32_e32 v142, v142
	v_exp_f32_e32 v143, v143
	v_add_f32_e32 v128, 1.0, v128
	v_add_f32_e32 v129, 1.0, v129
	v_add_f32_e32 v130, 1.0, v130
	v_add_f32_e32 v131, 1.0, v131
	v_add_f32_e32 v132, 1.0, v132
	v_add_f32_e32 v133, 1.0, v133
	v_add_f32_e32 v134, 1.0, v134
	v_add_f32_e32 v135, 1.0, v135
	v_add_f32_e32 v136, 1.0, v136
	v_add_f32_e32 v137, 1.0, v137
	v_add_f32_e32 v138, 1.0, v138
	v_add_f32_e32 v139, 1.0, v139
	v_add_f32_e32 v140, 1.0, v140
	v_add_f32_e32 v141, 1.0, v141
	v_add_f32_e32 v142, 1.0, v142
	v_add_f32_e32 v143, 1.0, v143
	v_rcp_f32_e32 v128, v128
	v_rcp_f32_e32 v129, v129
	v_rcp_f32_e32 v130, v130
	v_rcp_f32_e32 v131, v131
	v_rcp_f32_e32 v132, v132
	v_rcp_f32_e32 v133, v133
	v_rcp_f32_e32 v134, v134
	v_rcp_f32_e32 v135, v135
	v_rcp_f32_e32 v136, v136
	v_rcp_f32_e32 v137, v137
	v_rcp_f32_e32 v138, v138
	v_rcp_f32_e32 v139, v139
	v_rcp_f32_e32 v140, v140
	v_rcp_f32_e32 v141, v141
	v_rcp_f32_e32 v142, v142
	v_rcp_f32_e32 v143, v143
	v_mul_f32_e32 v112, v112, v128
	v_mul_f32_e32 v113, v113, v129
	v_mul_f32_e32 v114, v114, v130
	v_mul_f32_e32 v115, v115, v131
	v_mul_f32_e32 v116, v116, v132
	v_mul_f32_e32 v117, v117, v133
	v_mul_f32_e32 v118, v118, v134
	v_mul_f32_e32 v119, v119, v135
	v_mul_f32_e32 v120, v120, v136
	v_mul_f32_e32 v121, v121, v137
	v_mul_f32_e32 v122, v122, v138
	v_mul_f32_e32 v123, v123, v139
	v_mul_f32_e32 v124, v124, v140
	v_mul_f32_e32 v125, v125, v141
	v_mul_f32_e32 v126, v126, v142
	v_mul_f32_e32 v127, v127, v143
	v_mul_f32_e32 v112, v112, v96
	v_mul_f32_e32 v113, v113, v97
	v_mul_f32_e32 v114, v114, v98
	v_mul_f32_e32 v115, v115, v99
	v_mul_f32_e32 v116, v116, v100
	v_mul_f32_e32 v117, v117, v101
	v_mul_f32_e32 v118, v118, v102
	v_mul_f32_e32 v119, v119, v103
	v_mul_f32_e32 v120, v120, v104
	v_mul_f32_e32 v121, v121, v105
	v_mul_f32_e32 v122, v122, v106
	v_mul_f32_e32 v123, v123, v107
	v_mul_f32_e32 v124, v124, v108
	v_mul_f32_e32 v125, v125, v109
	v_mul_f32_e32 v126, v126, v110
	v_mul_f32_e32 v127, v127, v111
	v_mul_f32_e32 v144, 0xbfb8aa3b, v80
	v_mul_f32_e32 v145, 0xbfb8aa3b, v81
	v_mul_f32_e32 v146, 0xbfb8aa3b, v82
	v_mul_f32_e32 v147, 0xbfb8aa3b, v83
	v_mul_f32_e32 v148, 0xbfb8aa3b, v84
	v_mul_f32_e32 v149, 0xbfb8aa3b, v85
	v_mul_f32_e32 v150, 0xbfb8aa3b, v86
	v_mul_f32_e32 v151, 0xbfb8aa3b, v87
	v_mul_f32_e32 v152, 0xbfb8aa3b, v88
	v_mul_f32_e32 v153, 0xbfb8aa3b, v89
	v_mul_f32_e32 v154, 0xbfb8aa3b, v90
	v_mul_f32_e32 v155, 0xbfb8aa3b, v91
	v_mul_f32_e32 v156, 0xbfb8aa3b, v92
	v_mul_f32_e32 v157, 0xbfb8aa3b, v93
	v_mul_f32_e32 v158, 0xbfb8aa3b, v94
	v_mul_f32_e32 v159, 0xbfb8aa3b, v95
	v_exp_f32_e32 v144, v144
	v_exp_f32_e32 v145, v145
	v_exp_f32_e32 v146, v146
	v_exp_f32_e32 v147, v147
	v_exp_f32_e32 v148, v148
	v_exp_f32_e32 v149, v149
	v_exp_f32_e32 v150, v150
	v_exp_f32_e32 v151, v151
	v_exp_f32_e32 v152, v152
	v_exp_f32_e32 v153, v153
	v_exp_f32_e32 v154, v154
	v_exp_f32_e32 v155, v155
	v_exp_f32_e32 v156, v156
	v_exp_f32_e32 v157, v157
	v_exp_f32_e32 v158, v158
	v_exp_f32_e32 v159, v159
	v_add_f32_e32 v144, 1.0, v144
	v_add_f32_e32 v145, 1.0, v145
	v_add_f32_e32 v146, 1.0, v146
	v_add_f32_e32 v147, 1.0, v147
	v_add_f32_e32 v148, 1.0, v148
	v_add_f32_e32 v149, 1.0, v149
	v_add_f32_e32 v150, 1.0, v150
	v_add_f32_e32 v151, 1.0, v151
	v_add_f32_e32 v152, 1.0, v152
	v_add_f32_e32 v153, 1.0, v153
	v_add_f32_e32 v154, 1.0, v154
	v_add_f32_e32 v155, 1.0, v155
	v_add_f32_e32 v156, 1.0, v156
	v_add_f32_e32 v157, 1.0, v157
	v_add_f32_e32 v158, 1.0, v158
	v_add_f32_e32 v159, 1.0, v159
	v_rcp_f32_e32 v144, v144
	v_rcp_f32_e32 v145, v145
	v_rcp_f32_e32 v146, v146
	v_rcp_f32_e32 v147, v147
	v_rcp_f32_e32 v148, v148
	v_rcp_f32_e32 v149, v149
	v_rcp_f32_e32 v150, v150
	v_rcp_f32_e32 v151, v151
	v_rcp_f32_e32 v152, v152
	v_rcp_f32_e32 v153, v153
	v_rcp_f32_e32 v154, v154
	v_rcp_f32_e32 v155, v155
	v_rcp_f32_e32 v156, v156
	v_rcp_f32_e32 v157, v157
	v_rcp_f32_e32 v158, v158
	v_rcp_f32_e32 v159, v159
	v_mul_f32_e32 v80, v80, v144
	v_mul_f32_e32 v81, v81, v145
	v_mul_f32_e32 v82, v82, v146
	v_mul_f32_e32 v83, v83, v147
	v_mul_f32_e32 v84, v84, v148
	v_mul_f32_e32 v85, v85, v149
	v_mul_f32_e32 v86, v86, v150
	v_mul_f32_e32 v87, v87, v151
	v_mul_f32_e32 v88, v88, v152
	v_mul_f32_e32 v89, v89, v153
	v_mul_f32_e32 v90, v90, v154
	v_mul_f32_e32 v91, v91, v155
	v_mul_f32_e32 v92, v92, v156
	v_mul_f32_e32 v93, v93, v157
	v_mul_f32_e32 v94, v94, v158
	v_mul_f32_e32 v95, v95, v159
	v_mul_f32_e32 v80, v80, v64
	v_mul_f32_e32 v81, v81, v65
	v_mul_f32_e32 v82, v82, v66
	v_mul_f32_e32 v83, v83, v67
	v_mul_f32_e32 v84, v84, v68
	v_mul_f32_e32 v85, v85, v69
	v_mul_f32_e32 v86, v86, v70
	v_mul_f32_e32 v87, v87, v71
; DI unsigned pk_bf16(float lo, float hi) { f32x2v v = {lo, hi}; bf16x2v b = __builtin_convertvector(v, bf16x2v); return __builtin_bit_cast(unsigned, b); }
; DI float sigmoidf_(float x) { return 1.f / (1.f + __expf(-x)); }
; DI void lds_sync() { wait_lgkm0(); bar_(); }
; DI void phase9_10(const Params& p, char* smem) {
;     ...
;         for (int pr = 0; pr < 2; ++pr) {
;           char* d = tile + (wn * 64 + tn * 32 + r) * 272 + (wm * 64 + pr * 32 + 4 * hh) * 2;
; #pragma unroll
;           for (int q = 0; q < 4; ++q) {
;             float v[4];
; #pragma unroll
;             for (int j = 0; j < 4; ++j) { const float g = acc[2 * pr][tn][4 * q + j], uu = acc[2 * pr + 1][tn][4 * q + j]; v[j] = g * sigmoidf_(g) * uu; }
;             uint2 ou; ou.x = pk_bf16(v[0], v[1]); ou.y = pk_bf16(v[2], v[3]);
;             *(uint2*)(d + 16 * q) = ou;
;           }
;         }
;       lds_sync();
	v_mul_f32_e32 v88, v88, v72
	v_mul_f32_e32 v89, v89, v73
	v_mul_f32_e32 v90, v90, v74
	v_mul_f32_e32 v91, v91, v75
	v_mul_f32_e32 v92, v92, v76
	v_mul_f32_e32 v93, v93, v77
	v_mul_f32_e32 v94, v94, v78
	v_mul_f32_e32 v95, v95, v79
	v_mul_f32_e32 v128, 0xbfb8aa3b, v48
	v_mul_f32_e32 v129, 0xbfb8aa3b, v49
	v_mul_f32_e32 v130, 0xbfb8aa3b, v50
	v_mul_f32_e32 v131, 0xbfb8aa3b, v51
	v_mul_f32_e32 v132, 0xbfb8aa3b, v52
	v_mul_f32_e32 v133, 0xbfb8aa3b, v53
	v_mul_f32_e32 v134, 0xbfb8aa3b, v54
	v_mul_f32_e32 v135, 0xbfb8aa3b, v55
	v_mul_f32_e32 v136, 0xbfb8aa3b, v56
	v_mul_f32_e32 v137, 0xbfb8aa3b, v57
	v_mul_f32_e32 v138, 0xbfb8aa3b, v58
	v_mul_f32_e32 v139, 0xbfb8aa3b, v59
	v_mul_f32_e32 v140, 0xbfb8aa3b, v60
	v_mul_f32_e32 v141, 0xbfb8aa3b, v61
	v_mul_f32_e32 v142, 0xbfb8aa3b, v62
	v_mul_f32_e32 v143, 0xbfb8aa3b, v63
	v_exp_f32_e32 v128, v128
	v_exp_f32_e32 v129, v129
	v_exp_f32_e32 v130, v130
	v_exp_f32_e32 v131, v131
	v_exp_f32_e32 v132, v132
	v_exp_f32_e32 v133, v133
	v_exp_f32_e32 v134, v134
	v_exp_f32_e32 v135, v135
	v_exp_f32_e32 v136, v136
	v_exp_f32_e32 v137, v137
	v_exp_f32_e32 v138, v138
	v_exp_f32_e32 v139, v139
	v_exp_f32_e32 v140, v140
	v_exp_f32_e32 v141, v141
	v_exp_f32_e32 v142, v142
	v_exp_f32_e32 v143, v143
	v_add_f32_e32 v128, 1.0, v128
	v_add_f32_e32 v129, 1.0, v129
	v_add_f32_e32 v130, 1.0, v130
	v_add_f32_e32 v131, 1.0, v131
	v_add_f32_e32 v132, 1.0, v132
	v_add_f32_e32 v133, 1.0, v133
	v_add_f32_e32 v134, 1.0, v134
	v_add_f32_e32 v135, 1.0, v135
	v_add_f32_e32 v136, 1.0, v136
	v_add_f32_e32 v137, 1.0, v137
	v_add_f32_e32 v138, 1.0, v138
	v_add_f32_e32 v139, 1.0, v139
	v_add_f32_e32 v140, 1.0, v140
	v_add_f32_e32 v141, 1.0, v141
	v_add_f32_e32 v142, 1.0, v142
	v_add_f32_e32 v143, 1.0, v143
	v_rcp_f32_e32 v128, v128
	v_rcp_f32_e32 v129, v129
	v_rcp_f32_e32 v130, v130
	v_rcp_f32_e32 v131, v131
	v_rcp_f32_e32 v132, v132
	v_rcp_f32_e32 v133, v133
	v_rcp_f32_e32 v134, v134
	v_rcp_f32_e32 v135, v135
	v_rcp_f32_e32 v136, v136
	v_rcp_f32_e32 v137, v137
	v_rcp_f32_e32 v138, v138
	v_rcp_f32_e32 v139, v139
	v_rcp_f32_e32 v140, v140
	v_rcp_f32_e32 v141, v141
	v_rcp_f32_e32 v142, v142
	v_rcp_f32_e32 v143, v143
	v_mul_f32_e32 v48, v48, v128
	v_mul_f32_e32 v49, v49, v129
	v_mul_f32_e32 v50, v50, v130
	v_mul_f32_e32 v51, v51, v131
	v_mul_f32_e32 v52, v52, v132
	v_mul_f32_e32 v53, v53, v133
	v_mul_f32_e32 v54, v54, v134
	v_mul_f32_e32 v55, v55, v135
	v_mul_f32_e32 v56, v56, v136
	v_mul_f32_e32 v57, v57, v137
	v_mul_f32_e32 v58, v58, v138
	v_mul_f32_e32 v59, v59, v139
	v_mul_f32_e32 v60, v60, v140
	v_mul_f32_e32 v61, v61, v141
	v_mul_f32_e32 v62, v62, v142
	v_mul_f32_e32 v63, v63, v143
	v_mul_f32_e32 v48, v48, v32
	v_mul_f32_e32 v49, v49, v33
	v_mul_f32_e32 v50, v50, v34
	v_mul_f32_e32 v51, v51, v35
	v_mul_f32_e32 v52, v52, v36
	v_mul_f32_e32 v53, v53, v37
	v_mul_f32_e32 v54, v54, v38
	v_mul_f32_e32 v55, v55, v39
	v_mul_f32_e32 v56, v56, v40
	v_mul_f32_e32 v57, v57, v41
	v_mul_f32_e32 v58, v58, v42
	v_mul_f32_e32 v59, v59, v43
	v_mul_f32_e32 v60, v60, v44
	v_mul_f32_e32 v61, v61, v45
	v_mul_f32_e32 v62, v62, v46
	v_mul_f32_e32 v63, v63, v47
	v_mul_f32_e32 v144, 0xbfb8aa3b, v16
	v_mul_f32_e32 v145, 0xbfb8aa3b, v17
	v_mul_f32_e32 v146, 0xbfb8aa3b, v18
	v_mul_f32_e32 v147, 0xbfb8aa3b, v19
	v_mul_f32_e32 v148, 0xbfb8aa3b, v20
	v_mul_f32_e32 v149, 0xbfb8aa3b, v21
	v_mul_f32_e32 v150, 0xbfb8aa3b, v22
	v_mul_f32_e32 v151, 0xbfb8aa3b, v23
	v_mul_f32_e32 v152, 0xbfb8aa3b, v24
	v_mul_f32_e32 v153, 0xbfb8aa3b, v25
	v_mul_f32_e32 v154, 0xbfb8aa3b, v26
	v_mul_f32_e32 v155, 0xbfb8aa3b, v27
	v_mul_f32_e32 v156, 0xbfb8aa3b, v28
	v_mul_f32_e32 v157, 0xbfb8aa3b, v29
	v_mul_f32_e32 v158, 0xbfb8aa3b, v30
	v_mul_f32_e32 v159, 0xbfb8aa3b, v31
	v_exp_f32_e32 v144, v144
	v_exp_f32_e32 v145, v145
	v_exp_f32_e32 v146, v146
	v_exp_f32_e32 v147, v147
	v_exp_f32_e32 v148, v148
	v_exp_f32_e32 v149, v149
	v_exp_f32_e32 v150, v150
	v_exp_f32_e32 v151, v151
	v_exp_f32_e32 v152, v152
	v_exp_f32_e32 v153, v153
	v_exp_f32_e32 v154, v154
	v_exp_f32_e32 v155, v155
	v_exp_f32_e32 v156, v156
	v_exp_f32_e32 v157, v157
	v_exp_f32_e32 v158, v158
	v_exp_f32_e32 v159, v159
	v_add_f32_e32 v144, 1.0, v144
	v_add_f32_e32 v145, 1.0, v145
	v_add_f32_e32 v146, 1.0, v146
	v_add_f32_e32 v147, 1.0, v147
	v_add_f32_e32 v148, 1.0, v148
	v_add_f32_e32 v149, 1.0, v149
	v_add_f32_e32 v150, 1.0, v150
	v_add_f32_e32 v151, 1.0, v151
	v_add_f32_e32 v152, 1.0, v152
	v_add_f32_e32 v153, 1.0, v153
	v_add_f32_e32 v154, 1.0, v154
	v_add_f32_e32 v155, 1.0, v155
	v_add_f32_e32 v156, 1.0, v156
	v_add_f32_e32 v157, 1.0, v157
	v_add_f32_e32 v158, 1.0, v158
	v_add_f32_e32 v159, 1.0, v159
	v_rcp_f32_e32 v144, v144
	v_rcp_f32_e32 v145, v145
	v_rcp_f32_e32 v146, v146
	v_rcp_f32_e32 v147, v147
	v_rcp_f32_e32 v148, v148
	v_rcp_f32_e32 v149, v149
	v_rcp_f32_e32 v150, v150
	v_rcp_f32_e32 v151, v151
	v_rcp_f32_e32 v152, v152
	v_rcp_f32_e32 v153, v153
	v_rcp_f32_e32 v154, v154
	v_rcp_f32_e32 v155, v155
	v_rcp_f32_e32 v156, v156
	v_rcp_f32_e32 v157, v157
	v_rcp_f32_e32 v158, v158
	v_rcp_f32_e32 v159, v159
	v_mul_f32_e32 v16, v16, v144
	v_mul_f32_e32 v17, v17, v145
	v_mul_f32_e32 v18, v18, v146
	v_mul_f32_e32 v19, v19, v147
	v_mul_f32_e32 v20, v20, v148
	v_mul_f32_e32 v21, v21, v149
	v_mul_f32_e32 v22, v22, v150
	v_mul_f32_e32 v23, v23, v151
	v_mul_f32_e32 v24, v24, v152
	v_mul_f32_e32 v25, v25, v153
	v_mul_f32_e32 v26, v26, v154
	v_mul_f32_e32 v27, v27, v155
	v_mul_f32_e32 v28, v28, v156
	v_mul_f32_e32 v29, v29, v157
	v_mul_f32_e32 v30, v30, v158
	v_mul_f32_e32 v31, v31, v159
	v_mul_f32_e32 v16, v16, v0
	v_mul_f32_e32 v17, v17, v1
	v_mul_f32_e32 v18, v18, v2
	v_mul_f32_e32 v19, v19, v3
	v_mul_f32_e32 v20, v20, v4
	v_mul_f32_e32 v21, v21, v5
	v_mul_f32_e32 v22, v22, v6
	v_mul_f32_e32 v23, v23, v7
	v_mul_f32_e32 v24, v24, v8
	v_mul_f32_e32 v25, v25, v9
	v_mul_f32_e32 v26, v26, v10
	v_mul_f32_e32 v27, v27, v11
	v_mul_f32_e32 v28, v28, v12
	v_mul_f32_e32 v29, v29, v13
	v_mul_f32_e32 v30, v30, v14
	v_mul_f32_e32 v31, v31, v15
	s_waitcnt lgkmcnt(0)
	s_barrier
; DI unsigned pk_bf16(float lo, float hi) { f32x2v v = {lo, hi}; bf16x2v b = __builtin_convertvector(v, bf16x2v); return __builtin_bit_cast(unsigned, b); }
; DI float sigmoidf_(float x) { return 1.f / (1.f + __expf(-x)); }
; DI void lds_sync() { wait_lgkm0(); bar_(); }
; DI void phase9_10(const Params& p, char* smem) {
;     ...
;         for (int pr = 0; pr < 2; ++pr) {
;           char* d = tile + (wn * 64 + tn * 32 + r) * 272 + (wm * 64 + pr * 32 + 4 * hh) * 2;
; #pragma unroll
;           for (int q = 0; q < 4; ++q) {
;             float v[4];
; #pragma unroll
;             for (int j = 0; j < 4; ++j) { const float g = acc[2 * pr][tn][4 * q + j], uu = acc[2 * pr + 1][tn][4 * q + j]; v[j] = g * sigmoidf_(g) * uu; }
;             uint2 ou; ou.x = pk_bf16(v[0], v[1]); ou.y = pk_bf16(v[2], v[3]);
;             *(uint2*)(d + 16 * q) = ou;
;           }
;         }
;       lds_sync();
;       bf16_t* hd_ = p.hmid + (size_t)be * CAP * DE + ft * 128;
;       copy_tile(tile, 272, 256, 4, [&](int row) { return hd_ + (size_t)row * DE; }, 0, 16);
;     }
	s_waitcnt vmcnt(0)
	v_add_u32_e32 v160, 0x2000, v222
	v_cvt_pk_bf16_f32 v164, v112, v113
	v_cvt_pk_bf16_f32 v165, v114, v115
	v_cvt_pk_bf16_f32 v166, v116, v117
	v_cvt_pk_bf16_f32 v167, v118, v119
	v_cvt_pk_bf16_f32 v168, v120, v121
	v_cvt_pk_bf16_f32 v169, v122, v123
	v_cvt_pk_bf16_f32 v170, v124, v125
	v_cvt_pk_bf16_f32 v171, v126, v127
	ds_write2_b64 v222, v[164:165], v[166:167] offset1:2
	ds_write2_b64 v222, v[168:169], v[170:171] offset0:4 offset1:6
	v_cvt_pk_bf16_f32 v164, v80, v81
	v_cvt_pk_bf16_f32 v165, v82, v83
	v_cvt_pk_bf16_f32 v166, v84, v85
	v_cvt_pk_bf16_f32 v167, v86, v87
	v_cvt_pk_bf16_f32 v168, v88, v89
	v_cvt_pk_bf16_f32 v169, v90, v91
	v_cvt_pk_bf16_f32 v170, v92, v93
	v_cvt_pk_bf16_f32 v171, v94, v95
	ds_write2_b64 v222, v[164:165], v[166:167] offset0:8 offset1:10
	ds_write2_b64 v222, v[168:169], v[170:171] offset0:12 offset1:14
	v_cvt_pk_bf16_f32 v164, v48, v49
	v_cvt_pk_bf16_f32 v165, v50, v51
	v_cvt_pk_bf16_f32 v166, v52, v53
	v_cvt_pk_bf16_f32 v167, v54, v55
	v_cvt_pk_bf16_f32 v168, v56, v57
	v_cvt_pk_bf16_f32 v169, v58, v59
	v_cvt_pk_bf16_f32 v170, v60, v61
	v_cvt_pk_bf16_f32 v171, v62, v63
	ds_write2_b64 v160, v[164:165], v[166:167] offset0:64 offset1:66
	ds_write2_b64 v160, v[168:169], v[170:171] offset0:68 offset1:70
	v_cvt_pk_bf16_f32 v164, v16, v17
	v_cvt_pk_bf16_f32 v165, v18, v19
	v_cvt_pk_bf16_f32 v166, v20, v21
	v_cvt_pk_bf16_f32 v167, v22, v23
	v_cvt_pk_bf16_f32 v168, v24, v25
	v_cvt_pk_bf16_f32 v169, v26, v27
	v_cvt_pk_bf16_f32 v170, v28, v29
	v_cvt_pk_bf16_f32 v171, v30, v31
	ds_write2_b64 v160, v[164:165], v[166:167] offset0:72 offset1:74
	ds_write2_b64 v160, v[168:169], v[170:171] offset0:76 offset1:78
	s_waitcnt lgkmcnt(0)
	v_mov_b32_e32 v1, v220
	s_barrier
	s_nop 0
	v_cmp_gt_i32_e32 vcc, s69, v1
	s_and_saveexec_b64 s[4:5], vcc
	s_cbranch_execz .LBB0_1189
	s_lshl_b32 s6, s79, 8
	s_add_u32 s6, s77, s6
	v_lshlrev_b32_e32 v0, 4, v1
	s_addc_u32 s7, s78, 0
	v_and_b32_e32 v184, 0xf0, v0
	v_or_b32_e32 v0, 0x10000, v184
	v_lshl_add_u64 v[2:3], s[6:7], 0, v[184:185]
	s_mov_b64 s[6:7], 0
